# OUTPROJ epilogue half 0: the single vmcnt(0) after 16 residual loads replaced by counted waits per row group (12/10/8/6)
# speedup vs baseline: 1.0126x; 1.0126x over previous
.LBB0_364:
	ds_read_b128 v[128:131], v208
	ds_read_b128 v[132:135], v208 offset:1024
	ds_read_b128 v[136:139], v208 offset:2048
	ds_read_b128 v[140:143], v208 offset:3072
	s_add_u32 s24, s22, 0xfffc0080
	s_addc_u32 s25, s23, -1
	s_cmp_eq_u32 s51, 12
	s_cselect_b32 s29, s13, s25
	s_cselect_b32 s28, s21, s24
	s_cselect_b32 s25, s11, s50
	s_cselect_b32 s24, s48, s49
	v_lshl_add_u64 v[194:195], s[22:23], 0, v[184:185]
	s_add_i32 m0, s36, 0xc000
	ds_read_b128 v[144:147], v209
	ds_read_b128 v[148:151], v209 offset:1024
	ds_read_b128 v[152:155], v209 offset:2048
	ds_read_b128 v[156:159], v209 offset:3072
	ds_read_b128 v[160:163], v209 offset:4096
	ds_read_b128 v[164:167], v209 offset:5120
	ds_read_b128 v[168:171], v209 offset:6144
	ds_read_b128 v[172:175], v209 offset:7168
	global_load_lds_dwordx4 v[194:195], off
	v_lshl_add_u64 v[194:195], s[22:23], 0, v[186:187]
	s_add_i32 m0, s36, 0xe000
	s_nop 0
	global_load_lds_dwordx4 v[194:195], off
	s_waitcnt lgkmcnt(8)
	s_barrier
	s_waitcnt lgkmcnt(0)
	s_setprio 1
	s_waitcnt lgkmcnt(0)
	v_mfma_f32_16x16x32_bf16 v[124:127], v[128:131], v[144:147], v[124:127]
	v_mfma_f32_16x16x32_bf16 v[120:123], v[136:139], v[144:147], v[120:123]
	v_mfma_f32_16x16x32_bf16 v[108:111], v[128:131], v[152:155], v[108:111]
	v_mfma_f32_16x16x32_bf16 v[104:107], v[136:139], v[152:155], v[104:107]
	v_mfma_f32_16x16x32_bf16 v[92:95], v[128:131], v[160:163], v[92:95]
	v_mfma_f32_16x16x32_bf16 v[88:91], v[136:139], v[160:163], v[88:91]
	v_mfma_f32_16x16x32_bf16 v[76:79], v[128:131], v[168:171], v[76:79]
	v_mfma_f32_16x16x32_bf16 v[72:75], v[136:139], v[168:171], v[72:75]
	v_mfma_f32_16x16x32_bf16 v[124:127], v[132:135], v[148:151], v[124:127]
	v_mfma_f32_16x16x32_bf16 v[120:123], v[140:143], v[148:151], v[120:123]
	v_mfma_f32_16x16x32_bf16 v[108:111], v[132:135], v[156:159], v[108:111]
	v_mfma_f32_16x16x32_bf16 v[104:107], v[140:143], v[156:159], v[104:107]
	v_mfma_f32_16x16x32_bf16 v[92:95], v[132:135], v[164:167], v[92:95]
	v_mfma_f32_16x16x32_bf16 v[88:91], v[140:143], v[164:167], v[88:91]
	v_mfma_f32_16x16x32_bf16 v[76:79], v[132:135], v[172:175], v[76:79]
	v_mfma_f32_16x16x32_bf16 v[72:75], v[140:143], v[172:175], v[72:75]
	s_setprio 0
	s_barrier
	s_add_i32 s52, s45, s35
	v_lshl_add_u64 v[216:217], s[24:25], 0, v[178:179]
	s_mov_b32 m0, s52
	ds_read_b128 v[194:197], v210
	ds_read_b128 v[198:201], v210 offset:1024
	ds_read_b128 v[202:205], v210 offset:2048
	ds_read_b128 v[212:215], v210 offset:3072
	global_load_lds_dwordx4 v[216:217], off
	v_lshl_add_u64 v[218:219], s[24:25], 0, v[182:183]
	s_add_i32 m0, s52, 0x2000
	s_nop 0
	global_load_lds_dwordx4 v[218:219], off
	s_barrier
	s_waitcnt lgkmcnt(0)
	s_setprio 1
	s_waitcnt lgkmcnt(0)
	v_mfma_f32_16x16x32_bf16 v[116:119], v[194:197], v[144:147], v[116:119]
	v_mfma_f32_16x16x32_bf16 v[112:115], v[202:205], v[144:147], v[112:115]
	v_mfma_f32_16x16x32_bf16 v[100:103], v[194:197], v[152:155], v[100:103]
	v_mfma_f32_16x16x32_bf16 v[96:99], v[202:205], v[152:155], v[96:99]
	v_mfma_f32_16x16x32_bf16 v[84:87], v[194:197], v[160:163], v[84:87]
	v_mfma_f32_16x16x32_bf16 v[80:83], v[202:205], v[160:163], v[80:83]
	v_mfma_f32_16x16x32_bf16 v[68:71], v[194:197], v[168:171], v[68:71]
	v_mfma_f32_16x16x32_bf16 v[64:67], v[202:205], v[168:171], v[64:67]
	v_mfma_f32_16x16x32_bf16 v[116:119], v[198:201], v[148:151], v[116:119]
	v_mfma_f32_16x16x32_bf16 v[112:115], v[212:215], v[148:151], v[112:115]
	v_mfma_f32_16x16x32_bf16 v[100:103], v[198:201], v[156:159], v[100:103]
	v_mfma_f32_16x16x32_bf16 v[96:99], v[212:215], v[156:159], v[96:99]
	v_mfma_f32_16x16x32_bf16 v[84:87], v[198:201], v[164:167], v[84:87]
	v_mfma_f32_16x16x32_bf16 v[80:83], v[212:215], v[164:167], v[80:83]
	v_mfma_f32_16x16x32_bf16 v[68:71], v[198:201], v[172:175], v[68:71]
	v_mfma_f32_16x16x32_bf16 v[64:67], v[212:215], v[172:175], v[64:67]
	s_setprio 0
	s_mov_b32 m0, s36
	v_lshl_add_u64 v[220:221], s[28:29], 0, v[176:177]
	s_barrier
	ds_read_b128 v[144:147], v209 offset:16384
	ds_read_b128 v[148:151], v209 offset:17408
	ds_read_b128 v[152:155], v209 offset:18432
	ds_read_b128 v[156:159], v209 offset:19456
	ds_read_b128 v[160:163], v209 offset:20480
	ds_read_b128 v[164:167], v209 offset:21504
	ds_read_b128 v[168:171], v209 offset:22528
	ds_read_b128 v[172:175], v209 offset:23552
	global_load_lds_dwordx4 v[220:221], off
	v_lshl_add_u64 v[222:223], s[28:29], 0, v[180:181]
	s_mov_b32 m0, s37
	s_nop 0
	global_load_lds_dwordx4 v[222:223], off
	s_barrier
	s_waitcnt lgkmcnt(0)
	s_setprio 1
	s_waitcnt lgkmcnt(0)
	v_mfma_f32_16x16x32_bf16 v[60:63], v[128:131], v[144:147], v[60:63]
	v_mfma_f32_16x16x32_bf16 v[56:59], v[136:139], v[144:147], v[56:59]
	v_mfma_f32_16x16x32_bf16 v[44:47], v[128:131], v[152:155], v[44:47]
	v_mfma_f32_16x16x32_bf16 v[40:43], v[136:139], v[152:155], v[40:43]
	v_mfma_f32_16x16x32_bf16 v[28:31], v[128:131], v[160:163], v[28:31]
	v_mfma_f32_16x16x32_bf16 v[24:27], v[136:139], v[160:163], v[24:27]
	v_mfma_f32_16x16x32_bf16 v[12:15], v[128:131], v[168:171], v[12:15]
	v_mfma_f32_16x16x32_bf16 v[8:11], v[136:139], v[168:171], v[8:11]
	v_mfma_f32_16x16x32_bf16 v[60:63], v[132:135], v[148:151], v[60:63]
	v_mfma_f32_16x16x32_bf16 v[56:59], v[140:143], v[148:151], v[56:59]
	v_mfma_f32_16x16x32_bf16 v[44:47], v[132:135], v[156:159], v[44:47]
	v_mfma_f32_16x16x32_bf16 v[40:43], v[140:143], v[156:159], v[40:43]
	v_mfma_f32_16x16x32_bf16 v[28:31], v[132:135], v[164:167], v[28:31]
	v_mfma_f32_16x16x32_bf16 v[24:27], v[140:143], v[164:167], v[24:27]
	v_mfma_f32_16x16x32_bf16 v[12:15], v[132:135], v[172:175], v[12:15]
	v_mfma_f32_16x16x32_bf16 v[8:11], v[140:143], v[172:175], v[8:11]
	s_setprio 0
	s_barrier
	s_add_u32 s52, s24, 0x40000
	s_addc_u32 s53, s25, 0
	s_add_i32 s54, s46, s35
	v_lshl_add_u64 v[128:129], s[52:53], 0, v[178:179]
	s_mov_b32 m0, s54
	s_nop 0
	global_load_lds_dwordx4 v[128:129], off
	v_lshl_add_u64 v[128:129], s[52:53], 0, v[182:183]
	s_add_i32 m0, s54, 0x2000
	s_nop 0
	global_load_lds_dwordx4 v[128:129], off
	s_waitcnt vmcnt(6)
	s_barrier
	s_setprio 1
	v_mfma_f32_16x16x32_bf16 v[52:55], v[194:197], v[144:147], v[52:55]
	v_mfma_f32_16x16x32_bf16 v[48:51], v[202:205], v[144:147], v[48:51]
	v_mfma_f32_16x16x32_bf16 v[36:39], v[194:197], v[152:155], v[36:39]
	v_mfma_f32_16x16x32_bf16 v[32:35], v[202:205], v[152:155], v[32:35]
	v_mfma_f32_16x16x32_bf16 v[20:23], v[194:197], v[160:163], v[20:23]
	v_mfma_f32_16x16x32_bf16 v[16:19], v[202:205], v[160:163], v[16:19]
	v_mfma_f32_16x16x32_bf16 v[4:7], v[194:197], v[168:171], v[4:7]
	v_mfma_f32_16x16x32_bf16 v[0:3], v[202:205], v[168:171], v[0:3]
	v_mfma_f32_16x16x32_bf16 v[52:55], v[198:201], v[148:151], v[52:55]
	v_mfma_f32_16x16x32_bf16 v[48:51], v[212:215], v[148:151], v[48:51]
	v_mfma_f32_16x16x32_bf16 v[36:39], v[198:201], v[156:159], v[36:39]
	v_mfma_f32_16x16x32_bf16 v[32:35], v[212:215], v[156:159], v[32:35]
	v_mfma_f32_16x16x32_bf16 v[20:23], v[198:201], v[164:167], v[20:23]
	v_mfma_f32_16x16x32_bf16 v[16:19], v[212:215], v[164:167], v[16:19]
	v_mfma_f32_16x16x32_bf16 v[4:7], v[198:201], v[172:175], v[4:7]
	v_mfma_f32_16x16x32_bf16 v[0:3], v[212:215], v[172:175], v[0:3]
	s_setprio 0
	s_add_i32 s52, 0, 0x18000
	v_add_u32_e32 v140, s52, v206
	s_barrier
	ds_read_b128 v[128:131], v140
	ds_read_b128 v[132:135], v140 offset:1024
	ds_read_b128 v[136:139], v140 offset:2048
	ds_read_b128 v[140:143], v140 offset:3072
	s_add_u32 s28, s28, 0x40000
	s_addc_u32 s29, s29, 0
	s_mov_b32 m0, s38
	v_lshl_add_u64 v[194:195], s[28:29], 0, v[176:177]
	ds_read_b128 v[144:147], v209 offset:32768
	ds_read_b128 v[148:151], v209 offset:33792
	ds_read_b128 v[152:155], v209 offset:34816
	ds_read_b128 v[156:159], v209 offset:35840
	ds_read_b128 v[160:163], v209 offset:36864
	ds_read_b128 v[164:167], v209 offset:37888
	ds_read_b128 v[168:171], v209 offset:38912
	ds_read_b128 v[172:175], v209 offset:39936
	global_load_lds_dwordx4 v[194:195], off
	v_lshl_add_u64 v[194:195], s[28:29], 0, v[180:181]
	s_mov_b32 m0, s39
	s_nop 0
	global_load_lds_dwordx4 v[194:195], off
	s_waitcnt lgkmcnt(8)
	s_barrier
	s_waitcnt lgkmcnt(0)
	s_setprio 1
	s_waitcnt lgkmcnt(0)
	v_mfma_f32_16x16x32_bf16 v[124:127], v[128:131], v[144:147], v[124:127]
	v_mfma_f32_16x16x32_bf16 v[120:123], v[136:139], v[144:147], v[120:123]
	v_mfma_f32_16x16x32_bf16 v[108:111], v[128:131], v[152:155], v[108:111]
	v_mfma_f32_16x16x32_bf16 v[104:107], v[136:139], v[152:155], v[104:107]
	v_mfma_f32_16x16x32_bf16 v[92:95], v[128:131], v[160:163], v[92:95]
	v_mfma_f32_16x16x32_bf16 v[88:91], v[136:139], v[160:163], v[88:91]
	v_mfma_f32_16x16x32_bf16 v[76:79], v[128:131], v[168:171], v[76:79]
	v_mfma_f32_16x16x32_bf16 v[72:75], v[136:139], v[168:171], v[72:75]
	v_mfma_f32_16x16x32_bf16 v[124:127], v[132:135], v[148:151], v[124:127]
	v_mfma_f32_16x16x32_bf16 v[120:123], v[140:143], v[148:151], v[120:123]
	v_mfma_f32_16x16x32_bf16 v[108:111], v[132:135], v[156:159], v[108:111]
	v_mfma_f32_16x16x32_bf16 v[104:107], v[140:143], v[156:159], v[104:107]
	v_mfma_f32_16x16x32_bf16 v[92:95], v[132:135], v[164:167], v[92:95]
	v_mfma_f32_16x16x32_bf16 v[88:91], v[140:143], v[164:167], v[88:91]
	v_mfma_f32_16x16x32_bf16 v[76:79], v[132:135], v[172:175], v[76:79]
	v_mfma_f32_16x16x32_bf16 v[72:75], v[140:143], v[172:175], v[72:75]
	s_setprio 0
	s_barrier
	s_add_i32 s28, 0, 0x1c000
	s_add_i32 s29, s52, s35
	v_add_u32_e32 v212, s28, v206
	v_lshl_add_u64 v[216:217], v[216:217], 0, s[8:9]
	s_mov_b32 m0, s29
	ds_read_b128 v[194:197], v212
	ds_read_b128 v[198:201], v212 offset:1024
	ds_read_b128 v[202:205], v212 offset:2048
	ds_read_b128 v[212:215], v212 offset:3072
	global_load_lds_dwordx4 v[216:217], off
	v_lshl_add_u64 v[216:217], v[218:219], 0, s[8:9]
	s_add_i32 m0, s29, 0x2000
	s_nop 0
	global_load_lds_dwordx4 v[216:217], off
	s_barrier
	s_waitcnt lgkmcnt(0)
	s_setprio 1
	s_waitcnt lgkmcnt(0)
	v_mfma_f32_16x16x32_bf16 v[116:119], v[194:197], v[144:147], v[116:119]
	v_mfma_f32_16x16x32_bf16 v[112:115], v[202:205], v[144:147], v[112:115]
	v_mfma_f32_16x16x32_bf16 v[100:103], v[194:197], v[152:155], v[100:103]
	v_mfma_f32_16x16x32_bf16 v[96:99], v[202:205], v[152:155], v[96:99]
	v_mfma_f32_16x16x32_bf16 v[84:87], v[194:197], v[160:163], v[84:87]
	v_mfma_f32_16x16x32_bf16 v[80:83], v[202:205], v[160:163], v[80:83]
	v_mfma_f32_16x16x32_bf16 v[68:71], v[194:197], v[168:171], v[68:71]
	v_mfma_f32_16x16x32_bf16 v[64:67], v[202:205], v[168:171], v[64:67]
	v_mfma_f32_16x16x32_bf16 v[116:119], v[198:201], v[148:151], v[116:119]
	v_mfma_f32_16x16x32_bf16 v[112:115], v[212:215], v[148:151], v[112:115]
	v_mfma_f32_16x16x32_bf16 v[100:103], v[198:201], v[156:159], v[100:103]
	v_mfma_f32_16x16x32_bf16 v[96:99], v[212:215], v[156:159], v[96:99]
	v_mfma_f32_16x16x32_bf16 v[84:87], v[198:201], v[164:167], v[84:87]
	v_mfma_f32_16x16x32_bf16 v[80:83], v[212:215], v[164:167], v[80:83]
	v_mfma_f32_16x16x32_bf16 v[68:71], v[198:201], v[172:175], v[68:71]
	v_mfma_f32_16x16x32_bf16 v[64:67], v[212:215], v[172:175], v[64:67]
	s_setprio 0
	s_mov_b32 m0, s41
	v_lshl_add_u64 v[216:217], v[220:221], 0, s[8:9]
	s_barrier
	ds_read_b128 v[144:147], v209 offset:49152
	ds_read_b128 v[148:151], v209 offset:50176
	ds_read_b128 v[152:155], v209 offset:51200
	ds_read_b128 v[156:159], v209 offset:52224
	ds_read_b128 v[160:163], v209 offset:53248
	ds_read_b128 v[164:167], v209 offset:54272
	ds_read_b128 v[168:171], v209 offset:55296
	ds_read_b128 v[172:175], v209 offset:56320
	global_load_lds_dwordx4 v[216:217], off
	v_lshl_add_u64 v[216:217], v[222:223], 0, s[8:9]
	s_mov_b32 m0, s42
	s_nop 0
	global_load_lds_dwordx4 v[216:217], off
	s_barrier
	s_waitcnt lgkmcnt(0)
	s_setprio 1
	s_waitcnt lgkmcnt(0)
	v_mfma_f32_16x16x32_bf16 v[60:63], v[128:131], v[144:147], v[60:63]
	v_mfma_f32_16x16x32_bf16 v[56:59], v[136:139], v[144:147], v[56:59]
	v_mfma_f32_16x16x32_bf16 v[44:47], v[128:131], v[152:155], v[44:47]
	v_mfma_f32_16x16x32_bf16 v[40:43], v[136:139], v[152:155], v[40:43]
	v_mfma_f32_16x16x32_bf16 v[28:31], v[128:131], v[160:163], v[28:31]
	v_mfma_f32_16x16x32_bf16 v[24:27], v[136:139], v[160:163], v[24:27]
	v_mfma_f32_16x16x32_bf16 v[12:15], v[128:131], v[168:171], v[12:15]
	v_mfma_f32_16x16x32_bf16 v[8:11], v[136:139], v[168:171], v[8:11]
	v_mfma_f32_16x16x32_bf16 v[60:63], v[132:135], v[148:151], v[60:63]
	v_mfma_f32_16x16x32_bf16 v[56:59], v[140:143], v[148:151], v[56:59]
	v_mfma_f32_16x16x32_bf16 v[44:47], v[132:135], v[156:159], v[44:47]
	v_mfma_f32_16x16x32_bf16 v[40:43], v[140:143], v[156:159], v[40:43]
	v_mfma_f32_16x16x32_bf16 v[28:31], v[132:135], v[164:167], v[28:31]
	v_mfma_f32_16x16x32_bf16 v[24:27], v[140:143], v[164:167], v[24:27]
	v_mfma_f32_16x16x32_bf16 v[12:15], v[132:135], v[172:175], v[12:15]
	v_mfma_f32_16x16x32_bf16 v[8:11], v[140:143], v[172:175], v[8:11]
	s_setprio 0
	s_barrier
	s_add_u32 s24, s24, 0x40080
	s_addc_u32 s25, s25, 0
	s_add_i32 s28, s28, s35
	v_lshl_add_u64 v[128:129], s[24:25], 0, v[178:179]
	s_mov_b32 m0, s28
	s_nop 0
	global_load_lds_dwordx4 v[128:129], off
	v_lshl_add_u64 v[128:129], s[24:25], 0, v[182:183]
	s_add_i32 m0, s28, 0x2000
	s_nop 0
	global_load_lds_dwordx4 v[128:129], off
	s_waitcnt vmcnt(6)
	s_barrier
	s_setprio 1
	v_mfma_f32_16x16x32_bf16 v[52:55], v[194:197], v[144:147], v[52:55]
	v_mfma_f32_16x16x32_bf16 v[48:51], v[202:205], v[144:147], v[48:51]
	v_mfma_f32_16x16x32_bf16 v[36:39], v[194:197], v[152:155], v[36:39]
	v_mfma_f32_16x16x32_bf16 v[32:35], v[202:205], v[152:155], v[32:35]
	v_mfma_f32_16x16x32_bf16 v[20:23], v[194:197], v[160:163], v[20:23]
	v_mfma_f32_16x16x32_bf16 v[16:19], v[202:205], v[160:163], v[16:19]
	v_mfma_f32_16x16x32_bf16 v[4:7], v[194:197], v[168:171], v[4:7]
	v_mfma_f32_16x16x32_bf16 v[0:3], v[202:205], v[168:171], v[0:3]
	v_mfma_f32_16x16x32_bf16 v[52:55], v[198:201], v[148:151], v[52:55]
	v_mfma_f32_16x16x32_bf16 v[48:51], v[212:215], v[148:151], v[48:51]
	v_mfma_f32_16x16x32_bf16 v[36:39], v[198:201], v[156:159], v[36:39]
	v_mfma_f32_16x16x32_bf16 v[32:35], v[212:215], v[156:159], v[32:35]
	v_mfma_f32_16x16x32_bf16 v[20:23], v[198:201], v[164:167], v[20:23]
	v_mfma_f32_16x16x32_bf16 v[16:19], v[212:215], v[164:167], v[16:19]
	v_mfma_f32_16x16x32_bf16 v[4:7], v[198:201], v[172:175], v[4:7]
	v_mfma_f32_16x16x32_bf16 v[0:3], v[212:215], v[172:175], v[0:3]
	s_setprio 0
	s_add_i32 s51, s51, 2
	s_add_u32 s22, s22, 0x100
	s_addc_u32 s23, s23, 0
	s_add_u32 s49, s49, 0x100
	s_addc_u32 s50, s50, 0
	s_cmp_gt_u32 s51, 13
	s_barrier
	s_cbranch_scc0 .LBB0_364
	v_lshl_add_u32 v196, s20, 8, v189
	v_lshl_or_b32 v194, s6, 8, v207
	v_readlane_b32 s48, v235, 5
	v_ashrrev_i32_e32 v195, 31, v194
	v_readlane_b32 s49, v235, 6
	v_ashrrev_i32_e32 v197, 31, v196
	v_lshlrev_b64 v[128:129], 12, v[196:197]
	v_lshl_add_u64 v[198:199], v[194:195], 2, s[48:49]
	v_or_b32_e32 v204, 16, v196
	v_lshl_add_u64 v[128:129], v[198:199], 0, v[128:129]
	v_ashrrev_i32_e32 v205, 31, v204
	global_load_dwordx4 v[212:215], v[128:129], off offset:16 nt
	global_load_dwordx4 v[216:219], v[128:129], off nt
	global_load_dwordx4 v[220:223], v[128:129], off offset:528 nt
	global_load_dwordx4 v[224:227], v[128:129], off offset:512 nt
	v_lshlrev_b64 v[128:129], 12, v[204:205]
	v_or_b32_e32 v202, 32, v196
	v_lshl_add_u64 v[128:129], v[198:199], 0, v[128:129]
	v_ashrrev_i32_e32 v203, 31, v202
	global_load_dwordx4 v[168:171], v[128:129], off offset:16 nt
	global_load_dwordx4 v[172:175], v[128:129], off nt
	global_load_dwordx4 v[160:163], v[128:129], off offset:528 nt
	global_load_dwordx4 v[164:167], v[128:129], off offset:512 nt
	v_lshlrev_b64 v[128:129], 12, v[202:203]
	v_or_b32_e32 v200, 48, v196
	v_lshl_add_u64 v[128:129], v[198:199], 0, v[128:129]
	v_ashrrev_i32_e32 v201, 31, v200
	global_load_dwordx4 v[152:155], v[128:129], off offset:16 nt
	global_load_dwordx4 v[156:159], v[128:129], off nt
	global_load_dwordx4 v[144:147], v[128:129], off offset:528 nt
	global_load_dwordx4 v[148:151], v[128:129], off offset:512 nt
	v_lshlrev_b64 v[128:129], 12, v[200:201]
	v_lshl_add_u64 v[132:133], v[198:199], 0, v[128:129]
	global_load_dwordx4 v[136:139], v[132:133], off offset:16 nt
	global_load_dwordx4 v[140:143], v[132:133], off nt
	global_load_dwordx4 v[128:131], v[132:133], off offset:528 nt
	s_nop 0
	global_load_dwordx4 v[132:135], v[132:133], off offset:512 nt
	s_lshl_b32 s20, s6, 2
	s_ashr_i32 s21, s20, 31
	v_readlane_b32 s50, v235, 7
	v_readlane_b32 s51, v235, 8
	v_readlane_b32 s52, v235, 9
	v_readlane_b32 s53, v235, 10
	v_readlane_b32 s54, v235, 11
	v_readlane_b32 s55, v235, 12
	v_readlane_b32 s56, v235, 13
	v_readlane_b32 s57, v235, 14
	v_readlane_b32 s58, v235, 15
	v_readlane_b32 s59, v235, 16
	v_readlane_b32 s60, v235, 17
	v_readlane_b32 s61, v235, 18
	v_readlane_b32 s62, v235, 19
	v_readlane_b32 s63, v235, 20
	s_waitcnt vmcnt(12)
	v_pk_add_f32 v[126:127], v[126:127], v[218:219]
	v_pk_add_f32 v[124:125], v[124:125], v[216:217]
	v_pk_add_f32 v[214:215], v[122:123], v[214:215]
	v_mul_f32_e32 v122, v125, v125
	v_mul_f32_e32 v123, v127, v127
	v_pk_add_f32 v[120:121], v[120:121], v[212:213]
	v_fmac_f32_e32 v122, v124, v124
	v_fmac_f32_e32 v123, v126, v126
	v_add_f32_e32 v122, v122, v123
	v_mul_f32_e32 v123, v121, v121
	v_mul_f32_e32 v212, v215, v215
	v_fmac_f32_e32 v123, v120, v120
	v_fmac_f32_e32 v212, v214, v214
	v_pk_add_f32 v[118:119], v[118:119], v[226:227]
	v_pk_add_f32 v[116:117], v[116:117], v[224:225]
	v_add_f32_e32 v123, v123, v212
	v_pk_add_f32 v[212:213], v[112:113], v[220:221]
	v_mul_f32_e32 v112, v117, v117
	v_mul_f32_e32 v113, v119, v119
	v_add_f32_e32 v216, v122, v123
	v_cvt_pk_bf16_f32 v122, v124, v125
	v_cvt_pk_bf16_f32 v123, v126, v127
	v_pk_add_f32 v[126:127], v[114:115], v[222:223]
	v_fmac_f32_e32 v112, v116, v116
	v_fmac_f32_e32 v113, v118, v118
	v_add_f32_e32 v112, v112, v113
	v_mul_f32_e32 v113, v213, v213
	v_mul_f32_e32 v114, v127, v127
	v_fmac_f32_e32 v113, v212, v212
	v_fmac_f32_e32 v114, v126, v126
	v_add_f32_e32 v113, v113, v114
	v_add_f32_e32 v112, v112, v113
	v_and_b32_e32 v113, 64, v211
	v_cvt_pk_bf16_f32 v124, v120, v121
	v_add_f32_e32 v115, v216, v112
	v_xor_b32_e32 v112, 16, v211
	v_add_u32_e32 v121, 64, v113
	v_cmp_lt_i32_e32 vcc, v112, v121
	v_lshlrev_b64 v[228:229], 11, v[196:197]
	v_cvt_pk_bf16_f32 v125, v214, v215
	s_nop 0
	v_cndmask_b32_e32 v112, v211, v112, vcc
	v_lshlrev_b32_e32 v120, 2, v112
	ds_bpermute_b32 v216, v120, v115
	v_lshl_add_u64 v[112:113], s[64:65], 0, v[228:229]
	v_lshl_add_u64 v[214:215], v[194:195], 1, v[112:113]
	v_xor_b32_e32 v113, 32, v211
	v_cmp_lt_i32_e32 vcc, v113, v121
	s_waitcnt lgkmcnt(0)
	v_add_f32_e32 v112, v115, v216
	global_store_dwordx4 v[214:215], v[122:125], off
	v_cndmask_b32_e32 v113, v211, v113, vcc
	v_lshlrev_b32_e32 v121, 2, v113
	ds_bpermute_b32 v113, v121, v112
	v_cvt_pk_bf16_f32 v114, v116, v117
	v_cvt_pk_bf16_f32 v115, v118, v119
	v_cvt_pk_bf16_f32 v116, v212, v213
	v_cvt_pk_bf16_f32 v117, v126, v127
	global_store_dwordx4 v[214:215], v[114:117], off offset:256
	s_and_saveexec_b64 s[22:23], s[2:3]
	s_cbranch_execz .LBB0_367
	v_lshlrev_b64 v[114:115], 6, v[196:197]
	v_lshl_add_u64 v[114:115], s[74:75], 0, v[114:115]
	v_lshl_add_u64 v[114:115], s[20:21], 2, v[114:115]
	s_lshl_b32 s6, s40, 2
	v_lshl_add_u64 v[114:115], v[114:115], 0, s[6:7]
	s_waitcnt lgkmcnt(0)
	v_add_f32_e32 v112, v112, v113
	global_store_dword v[114:115], v112, off
.LBB0_367:
	s_waitcnt vmcnt(10)
	s_or_b64 exec, exec, s[22:23]
	v_pk_add_f32 v[110:111], v[110:111], v[174:175]
	v_pk_add_f32 v[108:109], v[108:109], v[172:173]
	v_pk_add_f32 v[114:115], v[106:107], v[170:171]
	v_pk_add_f32 v[106:107], v[104:105], v[168:169]
	v_mul_f32_e32 v104, v109, v109
	v_mul_f32_e32 v105, v111, v111
	v_fmac_f32_e32 v104, v108, v108
	v_fmac_f32_e32 v105, v110, v110
	v_add_f32_e32 v104, v104, v105
	v_mul_f32_e32 v105, v107, v107
	v_mul_f32_e32 v116, v115, v115
	v_fmac_f32_e32 v105, v106, v106
	v_fmac_f32_e32 v116, v114, v114
	v_add_f32_e32 v105, v105, v116
	v_pk_add_f32 v[102:103], v[102:103], v[166:167]
	v_pk_add_f32 v[100:101], v[100:101], v[164:165]
	v_add_f32_e32 v116, v104, v105
	v_cvt_pk_bf16_f32 v104, v108, v109
	v_cvt_pk_bf16_f32 v105, v110, v111
	v_pk_add_f32 v[110:111], v[96:97], v[160:161]
	v_mul_f32_e32 v96, v101, v101
	v_mul_f32_e32 v97, v103, v103
	v_pk_add_f32 v[108:109], v[98:99], v[162:163]
	v_fmac_f32_e32 v96, v100, v100
	v_fmac_f32_e32 v97, v102, v102
	v_add_f32_e32 v96, v96, v97
	v_mul_f32_e32 v97, v111, v111
	v_mul_f32_e32 v98, v109, v109
	v_fmac_f32_e32 v97, v110, v110
	v_fmac_f32_e32 v98, v108, v108
	v_add_f32_e32 v97, v97, v98
	v_add_f32_e32 v96, v96, v97
	v_add_f32_e32 v99, v116, v96
	v_cvt_pk_bf16_f32 v106, v106, v107
	v_cvt_pk_bf16_f32 v107, v114, v115
	ds_bpermute_b32 v114, v120, v99
	s_waitcnt lgkmcnt(1)
	v_lshlrev_b64 v[112:113], 11, v[204:205]
	v_lshl_add_u64 v[96:97], s[64:65], 0, v[112:113]
	v_lshl_add_u64 v[112:113], v[194:195], 1, v[96:97]
	global_store_dwordx4 v[112:113], v[104:107], off
	s_waitcnt lgkmcnt(0)
	v_add_f32_e32 v96, v99, v114
	ds_bpermute_b32 v97, v121, v96
	v_cvt_pk_bf16_f32 v98, v100, v101
	v_cvt_pk_bf16_f32 v99, v102, v103
	v_cvt_pk_bf16_f32 v100, v110, v111
	v_cvt_pk_bf16_f32 v101, v108, v109
	global_store_dwordx4 v[112:113], v[98:101], off offset:256
	s_and_saveexec_b64 s[22:23], s[2:3]
	s_cbranch_execz .LBB0_369
	v_lshlrev_b64 v[98:99], 6, v[204:205]
	v_lshl_add_u64 v[98:99], s[74:75], 0, v[98:99]
	v_lshl_add_u64 v[98:99], s[20:21], 2, v[98:99]
	s_lshl_b32 s6, s40, 2
	v_lshl_add_u64 v[98:99], v[98:99], 0, s[6:7]
	s_waitcnt lgkmcnt(0)
	v_add_f32_e32 v96, v96, v97
	global_store_dword v[98:99], v96, off
.LBB0_369:
	s_waitcnt vmcnt(8)
	s_or_b64 exec, exec, s[22:23]
	v_pk_add_f32 v[94:95], v[94:95], v[158:159]
	v_pk_add_f32 v[92:93], v[92:93], v[156:157]
	v_pk_add_f32 v[98:99], v[90:91], v[154:155]
	v_pk_add_f32 v[90:91], v[88:89], v[152:153]
	v_mul_f32_e32 v88, v93, v93
	v_mul_f32_e32 v89, v95, v95
	v_fmac_f32_e32 v88, v92, v92
	v_fmac_f32_e32 v89, v94, v94
	v_add_f32_e32 v88, v88, v89
	v_mul_f32_e32 v89, v91, v91
	v_mul_f32_e32 v100, v99, v99
	v_fmac_f32_e32 v89, v90, v90
	v_fmac_f32_e32 v100, v98, v98
	v_add_f32_e32 v89, v89, v100
	v_pk_add_f32 v[86:87], v[86:87], v[150:151]
	v_pk_add_f32 v[84:85], v[84:85], v[148:149]
	v_add_f32_e32 v100, v88, v89
	v_cvt_pk_bf16_f32 v88, v92, v93
	v_cvt_pk_bf16_f32 v89, v94, v95
	v_pk_add_f32 v[94:95], v[80:81], v[144:145]
	v_mul_f32_e32 v80, v85, v85
	v_mul_f32_e32 v81, v87, v87
	v_pk_add_f32 v[92:93], v[82:83], v[146:147]
	v_fmac_f32_e32 v80, v84, v84
	v_fmac_f32_e32 v81, v86, v86
	v_add_f32_e32 v80, v80, v81
	v_mul_f32_e32 v81, v95, v95
	v_mul_f32_e32 v82, v93, v93
	v_fmac_f32_e32 v81, v94, v94
	v_fmac_f32_e32 v82, v92, v92
	v_add_f32_e32 v81, v81, v82
	v_add_f32_e32 v80, v80, v81
	v_add_f32_e32 v83, v100, v80
	v_cvt_pk_bf16_f32 v90, v90, v91
	v_cvt_pk_bf16_f32 v91, v98, v99
	ds_bpermute_b32 v98, v120, v83
	s_waitcnt lgkmcnt(1)
	v_lshlrev_b64 v[96:97], 11, v[202:203]
	v_lshl_add_u64 v[80:81], s[64:65], 0, v[96:97]
	v_lshl_add_u64 v[96:97], v[194:195], 1, v[80:81]
	global_store_dwordx4 v[96:97], v[88:91], off
	s_waitcnt lgkmcnt(0)
	v_add_f32_e32 v80, v83, v98
	ds_bpermute_b32 v81, v121, v80
	v_cvt_pk_bf16_f32 v82, v84, v85
	v_cvt_pk_bf16_f32 v83, v86, v87
	v_cvt_pk_bf16_f32 v84, v94, v95
	v_cvt_pk_bf16_f32 v85, v92, v93
	global_store_dwordx4 v[96:97], v[82:85], off offset:256
	s_and_saveexec_b64 s[22:23], s[2:3]
	s_cbranch_execz .LBB0_371
	v_lshlrev_b64 v[82:83], 6, v[202:203]
	v_lshl_add_u64 v[82:83], s[74:75], 0, v[82:83]
	v_lshl_add_u64 v[82:83], s[20:21], 2, v[82:83]
	s_lshl_b32 s6, s40, 2
	v_lshl_add_u64 v[82:83], v[82:83], 0, s[6:7]
	s_waitcnt lgkmcnt(0)
	v_add_f32_e32 v80, v80, v81
	global_store_dword v[82:83], v80, off
.LBB0_371:
	s_waitcnt vmcnt(6)
	s_or_b64 exec, exec, s[22:23]
	v_pk_add_f32 v[78:79], v[78:79], v[142:143]
	v_pk_add_f32 v[76:77], v[76:77], v[140:141]
	v_pk_add_f32 v[82:83], v[74:75], v[138:139]
	v_pk_add_f32 v[74:75], v[72:73], v[136:137]
	v_mul_f32_e32 v72, v77, v77
	v_mul_f32_e32 v73, v79, v79
	v_fmac_f32_e32 v72, v76, v76
	v_fmac_f32_e32 v73, v78, v78
	v_add_f32_e32 v72, v72, v73
	v_mul_f32_e32 v73, v75, v75
	v_mul_f32_e32 v84, v83, v83
	v_fmac_f32_e32 v73, v74, v74
	v_fmac_f32_e32 v84, v82, v82
	v_add_f32_e32 v73, v73, v84
	v_pk_add_f32 v[70:71], v[70:71], v[134:135]
	v_pk_add_f32 v[68:69], v[68:69], v[132:133]
	v_add_f32_e32 v84, v72, v73
	v_cvt_pk_bf16_f32 v72, v76, v77
	v_cvt_pk_bf16_f32 v73, v78, v79
	v_pk_add_f32 v[78:79], v[64:65], v[128:129]
	v_mul_f32_e32 v64, v69, v69
	v_mul_f32_e32 v65, v71, v71
	v_pk_add_f32 v[76:77], v[66:67], v[130:131]
	v_fmac_f32_e32 v64, v68, v68
	v_fmac_f32_e32 v65, v70, v70
	v_add_f32_e32 v64, v64, v65
	v_mul_f32_e32 v65, v79, v79
	v_mul_f32_e32 v66, v77, v77
	v_fmac_f32_e32 v65, v78, v78
	v_fmac_f32_e32 v66, v76, v76
	v_add_f32_e32 v65, v65, v66
	v_add_f32_e32 v64, v64, v65
	v_add_f32_e32 v67, v84, v64
	v_cvt_pk_bf16_f32 v74, v74, v75
	v_cvt_pk_bf16_f32 v75, v82, v83
	ds_bpermute_b32 v82, v120, v67
	s_waitcnt lgkmcnt(1)
	v_lshlrev_b64 v[80:81], 11, v[200:201]
	v_lshl_add_u64 v[64:65], s[64:65], 0, v[80:81]
	v_lshl_add_u64 v[80:81], v[194:195], 1, v[64:65]
	global_store_dwordx4 v[80:81], v[72:75], off
	s_waitcnt lgkmcnt(0)
	v_add_f32_e32 v64, v67, v82
	ds_bpermute_b32 v65, v121, v64
	v_cvt_pk_bf16_f32 v66, v68, v69
	v_cvt_pk_bf16_f32 v67, v70, v71
	v_cvt_pk_bf16_f32 v68, v78, v79
	v_cvt_pk_bf16_f32 v69, v76, v77
	global_store_dwordx4 v[80:81], v[66:69], off offset:256
	s_and_saveexec_b64 s[22:23], s[2:3]
	s_cbranch_execz .LBB0_373
	v_lshlrev_b64 v[66:67], 6, v[200:201]
	v_lshl_add_u64 v[66:67], s[74:75], 0, v[66:67]
	v_lshl_add_u64 v[66:67], s[20:21], 2, v[66:67]
	s_lshl_b32 s6, s40, 2
	v_lshl_add_u64 v[66:67], v[66:67], 0, s[6:7]
	s_waitcnt lgkmcnt(0)
	v_add_f32_e32 v64, v64, v65
	global_store_dword v[66:67], v64, off
